# P7 and P2 main epilogues: bf16 stores widened the same way (permlane16_swap -> dwordx4), on top of P3 widening
# speedup vs baseline: 1.0338x; 1.0165x over previous
; __device__ __forceinline__ unsigned cvt_pk_bf16(float lo, float hi) { unsigned r; asm volatile("v_cvt_pk_bf16_f32 %0, %1, %2" : "=v"(r) : "v"(lo), "v"(hi)); return r; }
;     __device__ __forceinline__ void operator()(const f32x4 (&acc)[2][2][4][2], const pg8::Unit& u, int wr, int wc, int fr, int fq) const {
;     ...
;             for (int m = 0; m < 4; ++m) { const int row = row0 + ai * 128 + m * 16;
;                 if (row < MV) {
;                     const float* rp = (row < MPR) ? res_p + (size_t)row * DM : res_s + (size_t)(row - MPR) * DM;
;                     float s = 0.f;
; #pragma unroll
;                     for (int bj = 0; bj < 2; ++bj)
; #pragma unroll
;                         for (int n = 0; n < 2; ++n) { const int col = col0 + bj * 128 + n * 16; f32x4 r;
;                             if (RESB) { const u32x2 rw = *(const u32x2*)(resb + (size_t)row * DM + col); r = (f32x4){bf2f(rw.x & 0xffff), bf2f(rw.x >> 16), bf2f(rw.y & 0xffff), bf2f(rw.y >> 16)}; }
;                             else r = *(const f32x4*)(rp + col);
;                             const f32x4 v = r + acc[ai][bj][m][n] * scale;
;                             if (OUTF) *(f32x4*)(out + (size_t)row * DM + col) = v;
;                             else { u32x2 w; w.x = cvt_pk_bf16(v[0], v[1]); w.y = cvt_pk_bf16(v[2], v[3]); *(u32x2*)(outb + (size_t)row * DM + col) = w;
;                                 s += (v[0] * v[0] + v[1] * v[1]) + (v[2] * v[2] + v[3] * v[3]); } }
;                     if (!OUTF) { s += __shfl_xor(s, 16); s += __shfl_xor(s, 32); if (fq == 0) atomicAdd(ss + row, s); }
.LBB0_389:
	s_cmp_lt_i32 s95, 2
	s_cbranch_scc0 .LBB0_449
	v_lshl_add_u32 v182, s94, 8, v230
	v_lshl_or_b32 v184, s44, 8, v233
	v_lshlrev_b32_e32 v182, 11, v182
	v_lshl_add_u32 v182, v184, 1, v182
	v_lshlrev_b32_e32 v183, 1, v182
	v_bfe_u32 v187, v236, 4, 1
	v_mul_u32_u24_e32 v187, 24, v187
	v_add_u32_e32 v187, v187, v182
	global_load_dwordx4 v[134:137], v183, s[16:17]
	global_load_dwordx4 v[138:141], v183, s[16:17] offset:64
	global_load_dwordx4 v[142:145], v183, s[16:17] offset:512
	global_load_dwordx4 v[146:149], v183, s[16:17] offset:576
	v_add_u32_e32 v184, 0x10000, v183
	global_load_dwordx4 v[150:153], v184, s[16:17]
	global_load_dwordx4 v[154:157], v184, s[16:17] offset:64
	global_load_dwordx4 v[158:161], v184, s[16:17] offset:512
	global_load_dwordx4 v[162:165], v184, s[16:17] offset:576
	v_add_u32_e32 v184, 0x20000, v183
	global_load_dwordx4 v[166:169], v184, s[16:17]
	global_load_dwordx4 v[170:173], v184, s[16:17] offset:64
	global_load_dwordx4 v[174:177], v184, s[16:17] offset:512
	global_load_dwordx4 v[178:181], v184, s[16:17] offset:576
	s_waitcnt vmcnt(8)
	v_fma_f32 v78, v78, 0.5, v134
	v_fma_f32 v79, v79, 0.5, v135
	v_fma_f32 v80, v80, 0.5, v136
	v_fma_f32 v81, v81, 0.5, v137
	v_mul_f32_e32 v134, v79, v79
	v_mul_f32_e32 v135, v81, v81
	v_fmac_f32_e32 v134, v78, v78
	v_fmac_f32_e32 v135, v80, v80
	v_add_f32_e32 v134, v134, v135
	v_mov_b32_e32 v185, v134
	v_cvt_pk_bf16_f32 v78, v78, v79
	v_cvt_pk_bf16_f32 v79, v80, v81
	v_fma_f32 v70, v70, 0.5, v138
	v_fma_f32 v71, v71, 0.5, v139
	v_fma_f32 v72, v72, 0.5, v140
	v_fma_f32 v73, v73, 0.5, v141
	v_mul_f32_e32 v138, v71, v71
	v_mul_f32_e32 v139, v73, v73
	v_fmac_f32_e32 v138, v70, v70
	v_fmac_f32_e32 v139, v72, v72
	v_add_f32_e32 v138, v138, v139
	v_add_f32_e32 v185, v185, v138
	v_cvt_pk_bf16_f32 v80, v70, v71
	v_cvt_pk_bf16_f32 v81, v72, v73
	v_fma_f32 v62, v62, 0.5, v142
	v_fma_f32 v63, v63, 0.5, v143
	v_fma_f32 v64, v64, 0.5, v144
	v_fma_f32 v65, v65, 0.5, v145
	v_mul_f32_e32 v142, v63, v63
	v_mul_f32_e32 v143, v65, v65
	v_fmac_f32_e32 v142, v62, v62
	v_fmac_f32_e32 v143, v64, v64
	v_add_f32_e32 v142, v142, v143
	v_add_f32_e32 v185, v185, v142
	v_cvt_pk_bf16_f32 v62, v62, v63
	v_cvt_pk_bf16_f32 v63, v64, v65
	v_fma_f32 v54, v54, 0.5, v146
	v_fma_f32 v55, v55, 0.5, v147
	v_fma_f32 v56, v56, 0.5, v148
	v_fma_f32 v57, v57, 0.5, v149
	v_mul_f32_e32 v146, v55, v55
	v_mul_f32_e32 v147, v57, v57
	v_fmac_f32_e32 v146, v54, v54
	v_fmac_f32_e32 v147, v56, v56
	v_add_f32_e32 v146, v146, v147
	v_add_f32_e32 v185, v185, v146
	v_cvt_pk_bf16_f32 v64, v54, v55
	v_cvt_pk_bf16_f32 v65, v56, v57
	v_mov_b32_e32 v70, v185
	v_add_u32_e32 v184, 0x30000, v183
	global_load_dwordx4 v[134:137], v184, s[16:17]
	global_load_dwordx4 v[138:141], v184, s[16:17] offset:64
	global_load_dwordx4 v[142:145], v184, s[16:17] offset:512
	global_load_dwordx4 v[146:149], v184, s[16:17] offset:576
	s_nop 1
	v_permlane16_swap_b32_e32 v78, v80
	v_permlane16_swap_b32_e32 v79, v81
	v_permlane16_swap_b32_e32 v62, v64
	v_permlane16_swap_b32_e32 v63, v65
	global_store_dwordx4 v187, v[78:81], s[28:29]
	global_store_dwordx4 v187, v[62:65], s[28:29] offset:256
	s_waitcnt vmcnt(10)
	v_fma_f32 v58, v58, 0.5, v150
	v_fma_f32 v59, v59, 0.5, v151
	v_fma_f32 v60, v60, 0.5, v152
	v_fma_f32 v61, v61, 0.5, v153
	v_mul_f32_e32 v150, v59, v59
	v_mul_f32_e32 v151, v61, v61
	v_fmac_f32_e32 v150, v58, v58
	v_fmac_f32_e32 v151, v60, v60
	v_add_f32_e32 v150, v150, v151
	v_mov_b32_e32 v185, v150
	v_cvt_pk_bf16_f32 v58, v58, v59
	v_cvt_pk_bf16_f32 v59, v60, v61
	v_fma_f32 v50, v50, 0.5, v154
	v_fma_f32 v51, v51, 0.5, v155
	v_fma_f32 v52, v52, 0.5, v156
	v_fma_f32 v53, v53, 0.5, v157
	v_mul_f32_e32 v154, v51, v51
	v_mul_f32_e32 v155, v53, v53
	v_fmac_f32_e32 v154, v50, v50
	v_fmac_f32_e32 v155, v52, v52
	v_add_f32_e32 v154, v154, v155
	v_add_f32_e32 v185, v185, v154
	v_cvt_pk_bf16_f32 v60, v50, v51
	v_cvt_pk_bf16_f32 v61, v52, v53
	v_fma_f32 v46, v46, 0.5, v158
	v_fma_f32 v47, v47, 0.5, v159
	v_fma_f32 v48, v48, 0.5, v160
	v_fma_f32 v49, v49, 0.5, v161
	v_mul_f32_e32 v158, v47, v47
	v_mul_f32_e32 v159, v49, v49
	v_fmac_f32_e32 v158, v46, v46
	v_fmac_f32_e32 v159, v48, v48
	v_add_f32_e32 v158, v158, v159
	v_add_f32_e32 v185, v185, v158
	v_cvt_pk_bf16_f32 v46, v46, v47
	v_cvt_pk_bf16_f32 v47, v48, v49
	v_fma_f32 v34, v34, 0.5, v162
	v_fma_f32 v35, v35, 0.5, v163
	v_fma_f32 v36, v36, 0.5, v164
	v_fma_f32 v37, v37, 0.5, v165
	v_mul_f32_e32 v162, v35, v35
	v_mul_f32_e32 v163, v37, v37
	v_fmac_f32_e32 v162, v34, v34
	v_fmac_f32_e32 v163, v36, v36
	v_add_f32_e32 v162, v162, v163
	v_add_f32_e32 v185, v185, v162
	v_cvt_pk_bf16_f32 v48, v34, v35
	v_cvt_pk_bf16_f32 v49, v36, v37
	v_mov_b32_e32 v50, v185
	v_add_u32_e32 v184, 0x80000, v183
	global_load_dwordx4 v[150:153], v184, s[16:17]
	global_load_dwordx4 v[154:157], v184, s[16:17] offset:64
	global_load_dwordx4 v[158:161], v184, s[16:17] offset:512
	global_load_dwordx4 v[162:165], v184, s[16:17] offset:576
	v_add_u32_e32 v184, 0x8000, v187
	s_nop 1
	v_permlane16_swap_b32_e32 v58, v60
	v_permlane16_swap_b32_e32 v59, v61
	v_permlane16_swap_b32_e32 v46, v48
	v_permlane16_swap_b32_e32 v47, v49
	global_store_dwordx4 v184, v[58:61], s[28:29]
	global_store_dwordx4 v184, v[46:49], s[28:29] offset:256
	s_waitcnt vmcnt(12)
; __device__ __forceinline__ unsigned cvt_pk_bf16(float lo, float hi) { unsigned r; asm volatile("v_cvt_pk_bf16_f32 %0, %1, %2" : "=v"(r) : "v"(lo), "v"(hi)); return r; }
;     __device__ __forceinline__ void operator()(const f32x4 (&acc)[2][2][4][2], const pg8::Unit& u, int wr, int wc, int fr, int fq) const {
;     ...
;             for (int m = 0; m < 4; ++m) { const int row = row0 + ai * 128 + m * 16;
;                 if (row < MV) {
;                     const float* rp = (row < MPR) ? res_p + (size_t)row * DM : res_s + (size_t)(row - MPR) * DM;
;                     float s = 0.f;
; #pragma unroll
;                     for (int bj = 0; bj < 2; ++bj)
; #pragma unroll
;                         for (int n = 0; n < 2; ++n) { const int col = col0 + bj * 128 + n * 16; f32x4 r;
;                             if (RESB) { const u32x2 rw = *(const u32x2*)(resb + (size_t)row * DM + col); r = (f32x4){bf2f(rw.x & 0xffff), bf2f(rw.x >> 16), bf2f(rw.y & 0xffff), bf2f(rw.y >> 16)}; }
;                             else r = *(const f32x4*)(rp + col);
;                             const f32x4 v = r + acc[ai][bj][m][n] * scale;
;                             if (OUTF) *(f32x4*)(out + (size_t)row * DM + col) = v;
;                             else { u32x2 w; w.x = cvt_pk_bf16(v[0], v[1]); w.y = cvt_pk_bf16(v[2], v[3]); *(u32x2*)(outb + (size_t)row * DM + col) = w;
;                                 s += (v[0] * v[0] + v[1] * v[1]) + (v[2] * v[2] + v[3] * v[3]); } }
;                     if (!OUTF) { s += __shfl_xor(s, 16); s += __shfl_xor(s, 32); if (fq == 0) atomicAdd(ss + row, s); }
	v_fma_f32 v38, v38, 0.5, v166
	v_fma_f32 v39, v39, 0.5, v167
	v_fma_f32 v40, v40, 0.5, v168
	v_fma_f32 v41, v41, 0.5, v169
	v_mul_f32_e32 v166, v39, v39
	v_mul_f32_e32 v167, v41, v41
	v_fmac_f32_e32 v166, v38, v38
	v_fmac_f32_e32 v167, v40, v40
	v_add_f32_e32 v166, v166, v167
	v_mov_b32_e32 v185, v166
	v_cvt_pk_bf16_f32 v38, v38, v39
	v_cvt_pk_bf16_f32 v39, v40, v41
	v_fma_f32 v30, v30, 0.5, v170
	v_fma_f32 v31, v31, 0.5, v171
	v_fma_f32 v32, v32, 0.5, v172
	v_fma_f32 v33, v33, 0.5, v173
	v_mul_f32_e32 v170, v31, v31
	v_mul_f32_e32 v171, v33, v33
	v_fmac_f32_e32 v170, v30, v30
	v_fmac_f32_e32 v171, v32, v32
	v_add_f32_e32 v170, v170, v171
	v_add_f32_e32 v185, v185, v170
	v_cvt_pk_bf16_f32 v40, v30, v31
	v_cvt_pk_bf16_f32 v41, v32, v33
	v_fma_f32 v26, v26, 0.5, v174
	v_fma_f32 v27, v27, 0.5, v175
	v_fma_f32 v28, v28, 0.5, v176
	v_fma_f32 v29, v29, 0.5, v177
	v_mul_f32_e32 v174, v27, v27
	v_mul_f32_e32 v175, v29, v29
	v_fmac_f32_e32 v174, v26, v26
	v_fmac_f32_e32 v175, v28, v28
	v_add_f32_e32 v174, v174, v175
	v_add_f32_e32 v185, v185, v174
	v_cvt_pk_bf16_f32 v26, v26, v27
	v_cvt_pk_bf16_f32 v27, v28, v29
	v_fma_f32 v18, v18, 0.5, v178
	v_fma_f32 v19, v19, 0.5, v179
	v_fma_f32 v20, v20, 0.5, v180
	v_fma_f32 v21, v21, 0.5, v181
	v_mul_f32_e32 v178, v19, v19
	v_mul_f32_e32 v179, v21, v21
	v_fmac_f32_e32 v178, v18, v18
	v_fmac_f32_e32 v179, v20, v20
	v_add_f32_e32 v178, v178, v179
	v_add_f32_e32 v185, v185, v178
	v_cvt_pk_bf16_f32 v28, v18, v19
	v_cvt_pk_bf16_f32 v29, v20, v21
	v_mov_b32_e32 v30, v185
	v_add_u32_e32 v184, 0x90000, v183
	global_load_dwordx4 v[166:169], v184, s[16:17]
	global_load_dwordx4 v[170:173], v184, s[16:17] offset:64
	global_load_dwordx4 v[174:177], v184, s[16:17] offset:512
	global_load_dwordx4 v[178:181], v184, s[16:17] offset:576
	v_add_u32_e32 v184, 0x10000, v187
	s_nop 1
	v_permlane16_swap_b32_e32 v38, v40
	v_permlane16_swap_b32_e32 v39, v41
	v_permlane16_swap_b32_e32 v26, v28
	v_permlane16_swap_b32_e32 v27, v29
	global_store_dwordx4 v184, v[38:41], s[28:29]
	global_store_dwordx4 v184, v[26:29], s[28:29] offset:256
	s_waitcnt vmcnt(14)
	v_fma_f32 v22, v22, 0.5, v134
	v_fma_f32 v23, v23, 0.5, v135
	v_fma_f32 v24, v24, 0.5, v136
	v_fma_f32 v25, v25, 0.5, v137
	v_mul_f32_e32 v134, v23, v23
	v_mul_f32_e32 v135, v25, v25
	v_fmac_f32_e32 v134, v22, v22
	v_fmac_f32_e32 v135, v24, v24
	v_add_f32_e32 v134, v134, v135
	v_mov_b32_e32 v185, v134
	v_cvt_pk_bf16_f32 v22, v22, v23
	v_cvt_pk_bf16_f32 v23, v24, v25
	v_fma_f32 v14, v14, 0.5, v138
	v_fma_f32 v15, v15, 0.5, v139
	v_fma_f32 v16, v16, 0.5, v140
	v_fma_f32 v17, v17, 0.5, v141
	v_mul_f32_e32 v138, v15, v15
	v_mul_f32_e32 v139, v17, v17
	v_fmac_f32_e32 v138, v14, v14
	v_fmac_f32_e32 v139, v16, v16
	v_add_f32_e32 v138, v138, v139
	v_add_f32_e32 v185, v185, v138
	v_cvt_pk_bf16_f32 v24, v14, v15
	v_cvt_pk_bf16_f32 v25, v16, v17
	v_fma_f32 v10, v10, 0.5, v142
	v_fma_f32 v11, v11, 0.5, v143
	v_fma_f32 v12, v12, 0.5, v144
	v_fma_f32 v13, v13, 0.5, v145
	v_mul_f32_e32 v142, v11, v11
	v_mul_f32_e32 v143, v13, v13
	v_fmac_f32_e32 v142, v10, v10
	v_fmac_f32_e32 v143, v12, v12
	v_add_f32_e32 v142, v142, v143
	v_add_f32_e32 v185, v185, v142
	v_cvt_pk_bf16_f32 v10, v10, v11
	v_cvt_pk_bf16_f32 v11, v12, v13
	v_fma_f32 v6, v6, 0.5, v146
	v_fma_f32 v7, v7, 0.5, v147
	v_fma_f32 v8, v8, 0.5, v148
	v_fma_f32 v9, v9, 0.5, v149
	v_mul_f32_e32 v146, v7, v7
	v_mul_f32_e32 v147, v9, v9
	v_fmac_f32_e32 v146, v6, v6
	v_fmac_f32_e32 v147, v8, v8
	v_add_f32_e32 v146, v146, v147
	v_add_f32_e32 v185, v185, v146
	v_cvt_pk_bf16_f32 v12, v6, v7
	v_cvt_pk_bf16_f32 v13, v8, v9
	v_mov_b32_e32 v14, v185
	v_add_u32_e32 v184, 0xa0000, v183
	global_load_dwordx4 v[134:137], v184, s[16:17]
	global_load_dwordx4 v[138:141], v184, s[16:17] offset:64
	global_load_dwordx4 v[142:145], v184, s[16:17] offset:512
	global_load_dwordx4 v[146:149], v184, s[16:17] offset:576
	v_add_u32_e32 v184, 0x18000, v187
	s_nop 1
	v_permlane16_swap_b32_e32 v22, v24
	v_permlane16_swap_b32_e32 v23, v25
	v_permlane16_swap_b32_e32 v10, v12
	v_permlane16_swap_b32_e32 v11, v13
	global_store_dwordx4 v184, v[22:25], s[28:29]
	global_store_dwordx4 v184, v[10:13], s[28:29] offset:256
	s_waitcnt vmcnt(14)
	v_fma_f32 v130, v130, 0.5, v150
	v_fma_f32 v131, v131, 0.5, v151
	v_fma_f32 v132, v132, 0.5, v152
	v_fma_f32 v133, v133, 0.5, v153
	v_mul_f32_e32 v150, v131, v131
	v_mul_f32_e32 v151, v133, v133
	v_fmac_f32_e32 v150, v130, v130
	v_fmac_f32_e32 v151, v132, v132
	v_add_f32_e32 v150, v150, v151
	v_mov_b32_e32 v185, v150
	v_cvt_pk_bf16_f32 v130, v130, v131
	v_cvt_pk_bf16_f32 v131, v132, v133
	v_fma_f32 v126, v126, 0.5, v154
	v_fma_f32 v127, v127, 0.5, v155
	v_fma_f32 v128, v128, 0.5, v156
	v_fma_f32 v129, v129, 0.5, v157
	v_mul_f32_e32 v154, v127, v127
	v_mul_f32_e32 v155, v129, v129
	v_fmac_f32_e32 v154, v126, v126
	v_fmac_f32_e32 v155, v128, v128
	v_add_f32_e32 v154, v154, v155
	v_add_f32_e32 v185, v185, v154
	v_cvt_pk_bf16_f32 v132, v126, v127
	v_cvt_pk_bf16_f32 v133, v128, v129
	v_fma_f32 v122, v122, 0.5, v158
	v_fma_f32 v123, v123, 0.5, v159
	v_fma_f32 v124, v124, 0.5, v160
	v_fma_f32 v125, v125, 0.5, v161
	v_mul_f32_e32 v158, v123, v123
	v_mul_f32_e32 v159, v125, v125
	v_fmac_f32_e32 v158, v122, v122
	v_fmac_f32_e32 v159, v124, v124
	v_add_f32_e32 v158, v158, v159
	v_add_f32_e32 v185, v185, v158
	v_cvt_pk_bf16_f32 v122, v122, v123
	v_cvt_pk_bf16_f32 v123, v124, v125
	v_fma_f32 v118, v118, 0.5, v162
	v_fma_f32 v119, v119, 0.5, v163
	v_fma_f32 v120, v120, 0.5, v164
	v_fma_f32 v121, v121, 0.5, v165
	v_mul_f32_e32 v162, v119, v119
	v_mul_f32_e32 v163, v121, v121
	v_fmac_f32_e32 v162, v118, v118
	v_fmac_f32_e32 v163, v120, v120
	v_add_f32_e32 v162, v162, v163
	v_add_f32_e32 v185, v185, v162
	v_cvt_pk_bf16_f32 v124, v118, v119
	v_cvt_pk_bf16_f32 v125, v120, v121
	v_mov_b32_e32 v126, v185
	v_add_u32_e32 v184, 0xb0000, v183
	global_load_dwordx4 v[150:153], v184, s[16:17]
	global_load_dwordx4 v[154:157], v184, s[16:17] offset:64
	global_load_dwordx4 v[158:161], v184, s[16:17] offset:512
	global_load_dwordx4 v[162:165], v184, s[16:17] offset:576
	v_add_u32_e32 v184, 0x40000, v187
	s_nop 1
	v_permlane16_swap_b32_e32 v130, v132
	v_permlane16_swap_b32_e32 v131, v133
	v_permlane16_swap_b32_e32 v122, v124
	v_permlane16_swap_b32_e32 v123, v125
	global_store_dwordx4 v184, v[130:133], s[28:29]
	global_store_dwordx4 v184, v[122:125], s[28:29] offset:256
	s_waitcnt vmcnt(14)
; __device__ __forceinline__ unsigned cvt_pk_bf16(float lo, float hi) { unsigned r; asm volatile("v_cvt_pk_bf16_f32 %0, %1, %2" : "=v"(r) : "v"(lo), "v"(hi)); return r; }
;     __device__ __forceinline__ void operator()(const f32x4 (&acc)[2][2][4][2], const pg8::Unit& u, int wr, int wc, int fr, int fq) const {
;     ...
;             for (int m = 0; m < 4; ++m) { const int row = row0 + ai * 128 + m * 16;
;                 if (row < MV) {
;                     const float* rp = (row < MPR) ? res_p + (size_t)row * DM : res_s + (size_t)(row - MPR) * DM;
;                     float s = 0.f;
; #pragma unroll
;                     for (int bj = 0; bj < 2; ++bj)
; #pragma unroll
;                         for (int n = 0; n < 2; ++n) { const int col = col0 + bj * 128 + n * 16; f32x4 r;
;                             if (RESB) { const u32x2 rw = *(const u32x2*)(resb + (size_t)row * DM + col); r = (f32x4){bf2f(rw.x & 0xffff), bf2f(rw.x >> 16), bf2f(rw.y & 0xffff), bf2f(rw.y >> 16)}; }
;                             else r = *(const f32x4*)(rp + col);
;                             const f32x4 v = r + acc[ai][bj][m][n] * scale;
;                             if (OUTF) *(f32x4*)(out + (size_t)row * DM + col) = v;
;                             else { u32x2 w; w.x = cvt_pk_bf16(v[0], v[1]); w.y = cvt_pk_bf16(v[2], v[3]); *(u32x2*)(outb + (size_t)row * DM + col) = w;
;                                 s += (v[0] * v[0] + v[1] * v[1]) + (v[2] * v[2] + v[3] * v[3]); } }
;                     if (!OUTF) { s += __shfl_xor(s, 16); s += __shfl_xor(s, 32); if (fq == 0) atomicAdd(ss + row, s); }
	v_fma_f32 v114, v114, 0.5, v166
	v_fma_f32 v115, v115, 0.5, v167
	v_fma_f32 v116, v116, 0.5, v168
	v_fma_f32 v117, v117, 0.5, v169
	v_mul_f32_e32 v166, v115, v115
	v_mul_f32_e32 v167, v117, v117
	v_fmac_f32_e32 v166, v114, v114
	v_fmac_f32_e32 v167, v116, v116
	v_add_f32_e32 v166, v166, v167
	v_mov_b32_e32 v185, v166
	v_cvt_pk_bf16_f32 v114, v114, v115
	v_cvt_pk_bf16_f32 v115, v116, v117
	v_fma_f32 v110, v110, 0.5, v170
	v_fma_f32 v111, v111, 0.5, v171
	v_fma_f32 v112, v112, 0.5, v172
	v_fma_f32 v113, v113, 0.5, v173
	v_mul_f32_e32 v170, v111, v111
	v_mul_f32_e32 v171, v113, v113
	v_fmac_f32_e32 v170, v110, v110
	v_fmac_f32_e32 v171, v112, v112
	v_add_f32_e32 v170, v170, v171
	v_add_f32_e32 v185, v185, v170
	v_cvt_pk_bf16_f32 v116, v110, v111
	v_cvt_pk_bf16_f32 v117, v112, v113
	v_fma_f32 v106, v106, 0.5, v174
	v_fma_f32 v107, v107, 0.5, v175
	v_fma_f32 v108, v108, 0.5, v176
	v_fma_f32 v109, v109, 0.5, v177
	v_mul_f32_e32 v174, v107, v107
	v_mul_f32_e32 v175, v109, v109
	v_fmac_f32_e32 v174, v106, v106
	v_fmac_f32_e32 v175, v108, v108
	v_add_f32_e32 v174, v174, v175
	v_add_f32_e32 v185, v185, v174
	v_cvt_pk_bf16_f32 v106, v106, v107
	v_cvt_pk_bf16_f32 v107, v108, v109
	v_fma_f32 v102, v102, 0.5, v178
	v_fma_f32 v103, v103, 0.5, v179
	v_fma_f32 v104, v104, 0.5, v180
	v_fma_f32 v105, v105, 0.5, v181
	v_mul_f32_e32 v178, v103, v103
	v_mul_f32_e32 v179, v105, v105
	v_fmac_f32_e32 v178, v102, v102
	v_fmac_f32_e32 v179, v104, v104
	v_add_f32_e32 v178, v178, v179
	v_add_f32_e32 v185, v185, v178
	v_cvt_pk_bf16_f32 v108, v102, v103
	v_cvt_pk_bf16_f32 v109, v104, v105
	v_mov_b32_e32 v110, v185
	v_add_u32_e32 v184, 0x48000, v187
	s_nop 1
	v_permlane16_swap_b32_e32 v114, v116
	v_permlane16_swap_b32_e32 v115, v117
	v_permlane16_swap_b32_e32 v106, v108
	v_permlane16_swap_b32_e32 v107, v109
	global_store_dwordx4 v184, v[114:117], s[28:29]
	global_store_dwordx4 v184, v[106:109], s[28:29] offset:256
	s_waitcnt vmcnt(10)
	v_fma_f32 v98, v98, 0.5, v134
	v_fma_f32 v99, v99, 0.5, v135
	v_fma_f32 v100, v100, 0.5, v136
	v_fma_f32 v101, v101, 0.5, v137
	v_mul_f32_e32 v134, v99, v99
	v_mul_f32_e32 v135, v101, v101
	v_fmac_f32_e32 v134, v98, v98
	v_fmac_f32_e32 v135, v100, v100
	v_add_f32_e32 v134, v134, v135
	v_mov_b32_e32 v185, v134
	v_cvt_pk_bf16_f32 v98, v98, v99
	v_cvt_pk_bf16_f32 v99, v100, v101
	v_fma_f32 v94, v94, 0.5, v138
	v_fma_f32 v95, v95, 0.5, v139
	v_fma_f32 v96, v96, 0.5, v140
	v_fma_f32 v97, v97, 0.5, v141
	v_mul_f32_e32 v138, v95, v95
	v_mul_f32_e32 v139, v97, v97
	v_fmac_f32_e32 v138, v94, v94
	v_fmac_f32_e32 v139, v96, v96
	v_add_f32_e32 v138, v138, v139
	v_add_f32_e32 v185, v185, v138
	v_cvt_pk_bf16_f32 v100, v94, v95
	v_cvt_pk_bf16_f32 v101, v96, v97
	v_fma_f32 v90, v90, 0.5, v142
	v_fma_f32 v91, v91, 0.5, v143
	v_fma_f32 v92, v92, 0.5, v144
	v_fma_f32 v93, v93, 0.5, v145
	v_mul_f32_e32 v142, v91, v91
	v_mul_f32_e32 v143, v93, v93
	v_fmac_f32_e32 v142, v90, v90
	v_fmac_f32_e32 v143, v92, v92
	v_add_f32_e32 v142, v142, v143
	v_add_f32_e32 v185, v185, v142
	v_cvt_pk_bf16_f32 v90, v90, v91
	v_cvt_pk_bf16_f32 v91, v92, v93
	v_fma_f32 v86, v86, 0.5, v146
	v_fma_f32 v87, v87, 0.5, v147
	v_fma_f32 v88, v88, 0.5, v148
	v_fma_f32 v89, v89, 0.5, v149
	v_mul_f32_e32 v146, v87, v87
	v_mul_f32_e32 v147, v89, v89
	v_fmac_f32_e32 v146, v86, v86
	v_fmac_f32_e32 v147, v88, v88
	v_add_f32_e32 v146, v146, v147
	v_add_f32_e32 v185, v185, v146
	v_cvt_pk_bf16_f32 v92, v86, v87
	v_cvt_pk_bf16_f32 v93, v88, v89
	v_mov_b32_e32 v94, v185
	v_add_u32_e32 v184, 0x50000, v187
	s_nop 1
	v_permlane16_swap_b32_e32 v98, v100
	v_permlane16_swap_b32_e32 v99, v101
	v_permlane16_swap_b32_e32 v90, v92
	v_permlane16_swap_b32_e32 v91, v93
	global_store_dwordx4 v184, v[98:101], s[28:29]
	global_store_dwordx4 v184, v[90:93], s[28:29] offset:256
	s_waitcnt vmcnt(6)
; __device__ __forceinline__ unsigned cvt_pk_bf16(float lo, float hi) { unsigned r; asm volatile("v_cvt_pk_bf16_f32 %0, %1, %2" : "=v"(r) : "v"(lo), "v"(hi)); return r; }
;     __device__ __forceinline__ void operator()(const f32x4 (&acc)[2][2][4][2], const pg8::Unit& u, int wr, int wc, int fr, int fq) const {
;     ...
;                         for (int n = 0; n < 2; ++n) { const int col = col0 + bj * 128 + n * 16; f32x4 r;
;                             if (RESB) { const u32x2 rw = *(const u32x2*)(resb + (size_t)row * DM + col); r = (f32x4){bf2f(rw.x & 0xffff), bf2f(rw.x >> 16), bf2f(rw.y & 0xffff), bf2f(rw.y >> 16)}; }
;                             else r = *(const f32x4*)(rp + col);
;                             const f32x4 v = r + acc[ai][bj][m][n] * scale;
;                             if (OUTF) *(f32x4*)(out + (size_t)row * DM + col) = v;
;                             else { u32x2 w; w.x = cvt_pk_bf16(v[0], v[1]); w.y = cvt_pk_bf16(v[2], v[3]); *(u32x2*)(outb + (size_t)row * DM + col) = w;
;                                 s += (v[0] * v[0] + v[1] * v[1]) + (v[2] * v[2] + v[3] * v[3]); } }
;                     if (!OUTF) { s += __shfl_xor(s, 16); s += __shfl_xor(s, 32); if (fq == 0) atomicAdd(ss + row, s); }
;                 }
	v_fma_f32 v82, v82, 0.5, v150
	v_fma_f32 v83, v83, 0.5, v151
	v_fma_f32 v84, v84, 0.5, v152
	v_fma_f32 v85, v85, 0.5, v153
	v_mul_f32_e32 v150, v83, v83
	v_mul_f32_e32 v151, v85, v85
	v_fmac_f32_e32 v150, v82, v82
	v_fmac_f32_e32 v151, v84, v84
	v_add_f32_e32 v150, v150, v151
	v_mov_b32_e32 v185, v150
	v_cvt_pk_bf16_f32 v82, v82, v83
	v_cvt_pk_bf16_f32 v83, v84, v85
	v_fma_f32 v74, v74, 0.5, v154
	v_fma_f32 v75, v75, 0.5, v155
	v_fma_f32 v76, v76, 0.5, v156
	v_fma_f32 v77, v77, 0.5, v157
	v_mul_f32_e32 v154, v75, v75
	v_mul_f32_e32 v155, v77, v77
	v_fmac_f32_e32 v154, v74, v74
	v_fmac_f32_e32 v155, v76, v76
	v_add_f32_e32 v154, v154, v155
	v_add_f32_e32 v185, v185, v154
	v_cvt_pk_bf16_f32 v84, v74, v75
	v_cvt_pk_bf16_f32 v85, v76, v77
	v_fma_f32 v66, v66, 0.5, v158
	v_fma_f32 v67, v67, 0.5, v159
	v_fma_f32 v68, v68, 0.5, v160
	v_fma_f32 v69, v69, 0.5, v161
	v_mul_f32_e32 v158, v67, v67
	v_mul_f32_e32 v159, v69, v69
	v_fmac_f32_e32 v158, v66, v66
	v_fmac_f32_e32 v159, v68, v68
	v_add_f32_e32 v158, v158, v159
	v_add_f32_e32 v185, v185, v158
	v_cvt_pk_bf16_f32 v66, v66, v67
	v_cvt_pk_bf16_f32 v67, v68, v69
	v_fma_f32 v42, v42, 0.5, v162
	v_fma_f32 v43, v43, 0.5, v163
	v_fma_f32 v44, v44, 0.5, v164
	v_fma_f32 v45, v45, 0.5, v165
	v_mul_f32_e32 v162, v43, v43
	v_mul_f32_e32 v163, v45, v45
	v_fmac_f32_e32 v162, v42, v42
	v_fmac_f32_e32 v163, v44, v44
	v_add_f32_e32 v162, v162, v163
	v_add_f32_e32 v185, v185, v162
	v_cvt_pk_bf16_f32 v68, v42, v43
	v_cvt_pk_bf16_f32 v69, v44, v45
	v_mov_b32_e32 v74, v185
	v_add_u32_e32 v184, 0x58000, v187
	s_nop 1
	v_permlane16_swap_b32_e32 v82, v84
	v_permlane16_swap_b32_e32 v83, v85
	v_permlane16_swap_b32_e32 v66, v68
	v_permlane16_swap_b32_e32 v67, v69
	global_store_dwordx4 v184, v[82:85], s[28:29]
	global_store_dwordx4 v184, v[66:69], s[28:29] offset:256
	v_xor_b32_e32 v186, 16, v236
	v_lshlrev_b32_e32 v186, 2, v186
	ds_bpermute_b32 v71, v186, v70
	ds_bpermute_b32 v51, v186, v50
	ds_bpermute_b32 v31, v186, v30
	ds_bpermute_b32 v15, v186, v14
	ds_bpermute_b32 v127, v186, v126
	ds_bpermute_b32 v111, v186, v110
	ds_bpermute_b32 v95, v186, v94
	ds_bpermute_b32 v75, v186, v74
	s_waitcnt lgkmcnt(0)
	v_add_f32_e32 v70, v70, v71
	v_add_f32_e32 v50, v50, v51
	v_add_f32_e32 v30, v30, v31
	v_add_f32_e32 v14, v14, v15
	v_add_f32_e32 v126, v126, v127
	v_add_f32_e32 v110, v110, v111
	v_add_f32_e32 v94, v94, v95
	v_add_f32_e32 v74, v74, v75
	v_xor_b32_e32 v186, 32, v236
	v_lshlrev_b32_e32 v186, 2, v186
	ds_bpermute_b32 v71, v186, v70
	ds_bpermute_b32 v51, v186, v50
	ds_bpermute_b32 v31, v186, v30
	ds_bpermute_b32 v15, v186, v14
	ds_bpermute_b32 v127, v186, v126
	ds_bpermute_b32 v111, v186, v110
	ds_bpermute_b32 v95, v186, v94
	ds_bpermute_b32 v75, v186, v74
	s_waitcnt lgkmcnt(0)
	v_add_f32_e32 v70, v70, v71
	v_add_f32_e32 v50, v50, v51
	v_add_f32_e32 v30, v30, v31
	v_add_f32_e32 v14, v14, v15
	v_add_f32_e32 v126, v126, v127
	v_add_f32_e32 v110, v110, v111
	v_add_f32_e32 v94, v94, v95
	v_add_f32_e32 v74, v74, v75
	v_lshl_add_u32 v182, s94, 8, v230
	v_lshlrev_b32_e32 v182, 2, v182
	s_and_saveexec_b64 s[0:1], s[8:9]
	global_atomic_add_f32 v182, v70, s[30:31]
	global_atomic_add_f32 v182, v50, s[30:31] offset:64
	global_atomic_add_f32 v182, v30, s[30:31] offset:128
	global_atomic_add_f32 v182, v14, s[30:31] offset:192
	global_atomic_add_f32 v182, v126, s[30:31] offset:512
	global_atomic_add_f32 v182, v110, s[30:31] offset:576
	global_atomic_add_f32 v182, v94, s[30:31] offset:640
	global_atomic_add_f32 v182, v74, s[30:31] offset:704
	s_or_b64 exec, exec, s[0:1]
	s_branch .Lp2e_done

; __device__ __forceinline__ unsigned cvt_pk_bf16(float lo, float hi) { unsigned r; asm volatile("v_cvt_pk_bf16_f32 %0, %1, %2" : "=v"(r) : "v"(lo), "v"(hi)); return r; }
;     __device__ __forceinline__ void operator()(const f32x4 (&acc)[2][2][4][2], const pg8::Unit& u, int wr, int wc, int fr, int fq) const {
;         const int row0 = u.pm * 256 + wr * 64 + fr, col0 = u.pn * 256 + wc * 32 + 4 * fq;
; #pragma unroll
;         for (int ai = 0; ai < 2; ++ai)
; #pragma unroll
;             for (int m = 0; m < 4; ++m) { const int row = row0 + ai * 128 + m * 16;
;                 if (row < MV) {
;                     const float* rp = (row < MPR) ? res_p + (size_t)row * DM : res_s + (size_t)(row - MPR) * DM;
;                     float s = 0.f;
; #pragma unroll
;                     for (int bj = 0; bj < 2; ++bj)
; #pragma unroll
;                         for (int n = 0; n < 2; ++n) { const int col = col0 + bj * 128 + n * 16; f32x4 r;
;                             if (RESB) { const u32x2 rw = *(const u32x2*)(resb + (size_t)row * DM + col); r = (f32x4){bf2f(rw.x & 0xffff), bf2f(rw.x >> 16), bf2f(rw.y & 0xffff), bf2f(rw.y >> 16)}; }
;                             else r = *(const f32x4*)(rp + col);
;                             const f32x4 v = r + acc[ai][bj][m][n] * scale;
;                             if (OUTF) *(f32x4*)(out + (size_t)row * DM + col) = v;
;                             else { u32x2 w; w.x = cvt_pk_bf16(v[0], v[1]); w.y = cvt_pk_bf16(v[2], v[3]); *(u32x2*)(outb + (size_t)row * DM + col) = w;
;                                 s += (v[0] * v[0] + v[1] * v[1]) + (v[2] * v[2] + v[3] * v[3]); } }
;                     if (!OUTF) { s += __shfl_xor(s, 16); s += __shfl_xor(s, 32); if (fq == 0) atomicAdd(ss + row, s); }
.LBB0_1056:
	s_cmp_lt_i32 s76, 2
	s_cbranch_scc0 .LBB0_1086
	v_lshl_add_u32 v160, s46, 8, v164
	v_lshl_or_b32 v161, s44, 8, v166
	v_lshlrev_b32_e32 v160, 11, v160
	v_lshl_add_u32 v160, v161, 1, v160
	v_bfe_u32 v174, v170, 4, 1
	v_mul_u32_u24_e32 v174, 24, v174
	v_add_u32_e32 v174, v174, v160
	global_load_dwordx2 v[176:177], v160, s[16:17]
	global_load_dwordx2 v[178:179], v160, s[16:17] offset:32
	global_load_dwordx2 v[180:181], v160, s[16:17] offset:256
	global_load_dwordx2 v[182:183], v160, s[16:17] offset:288
	v_add_u32_e32 v161, 0x8000, v160
	global_load_dwordx2 v[184:185], v161, s[16:17]
	global_load_dwordx2 v[186:187], v161, s[16:17] offset:32
	global_load_dwordx2 v[188:189], v161, s[16:17] offset:256
	global_load_dwordx2 v[190:191], v161, s[16:17] offset:288
	v_add_u32_e32 v161, 0x10000, v160
	global_load_dwordx2 v[192:193], v161, s[16:17]
	global_load_dwordx2 v[194:195], v161, s[16:17] offset:32
	global_load_dwordx2 v[196:197], v161, s[16:17] offset:256
	global_load_dwordx2 v[198:199], v161, s[16:17] offset:288
	v_add_u32_e32 v161, 0x18000, v160
	global_load_dwordx2 v[200:201], v161, s[16:17]
	global_load_dwordx2 v[202:203], v161, s[16:17] offset:32
	global_load_dwordx2 v[204:205], v161, s[16:17] offset:256
	global_load_dwordx2 v[206:207], v161, s[16:17] offset:288
	v_add_u32_e32 v161, 0x40000, v160
	global_load_dwordx2 v[208:209], v161, s[16:17]
	global_load_dwordx2 v[210:211], v161, s[16:17] offset:32
	global_load_dwordx2 v[212:213], v161, s[16:17] offset:256
	global_load_dwordx2 v[214:215], v161, s[16:17] offset:288
	v_add_u32_e32 v161, 0x48000, v160
	global_load_dwordx2 v[144:145], v161, s[16:17]
	global_load_dwordx2 v[146:147], v161, s[16:17] offset:32
	global_load_dwordx2 v[148:149], v161, s[16:17] offset:256
	global_load_dwordx2 v[150:151], v161, s[16:17] offset:288
	v_add_u32_e32 v161, 0x50000, v160
	global_load_dwordx2 v[152:153], v161, s[16:17]
	global_load_dwordx2 v[154:155], v161, s[16:17] offset:32
	global_load_dwordx2 v[156:157], v161, s[16:17] offset:256
	global_load_dwordx2 v[158:159], v161, s[16:17] offset:288
	s_waitcnt vmcnt(24)
	v_and_b32_e32 v162, 0xffff0000, v176
	v_lshlrev_b32_e32 v176, 16, v176
	v_and_b32_e32 v163, 0xffff0000, v177
	v_lshlrev_b32_e32 v177, 16, v177
	v_add_f32_e32 v64, v64, v176
	v_add_f32_e32 v65, v65, v162
	v_add_f32_e32 v66, v66, v177
	v_add_f32_e32 v67, v67, v163
	v_mul_f32_e32 v176, v65, v65
	v_mul_f32_e32 v177, v67, v67
	v_fmac_f32_e32 v176, v64, v64
	v_fmac_f32_e32 v177, v66, v66
	v_add_f32_e32 v176, v176, v177
	v_mov_b32_e32 v172, v176
	v_cvt_pk_bf16_f32 v64, v64, v65
	v_cvt_pk_bf16_f32 v65, v66, v67
	v_and_b32_e32 v162, 0xffff0000, v178
	v_lshlrev_b32_e32 v178, 16, v178
	v_and_b32_e32 v163, 0xffff0000, v179
	v_lshlrev_b32_e32 v179, 16, v179
	v_add_f32_e32 v60, v60, v178
	v_add_f32_e32 v61, v61, v162
	v_add_f32_e32 v62, v62, v179
	v_add_f32_e32 v63, v63, v163
	v_mul_f32_e32 v178, v61, v61
	v_mul_f32_e32 v179, v63, v63
	v_fmac_f32_e32 v178, v60, v60
	v_fmac_f32_e32 v179, v62, v62
	v_add_f32_e32 v178, v178, v179
	v_add_f32_e32 v172, v172, v178
	v_cvt_pk_bf16_f32 v66, v60, v61
	v_cvt_pk_bf16_f32 v67, v62, v63
	v_and_b32_e32 v162, 0xffff0000, v180
	v_lshlrev_b32_e32 v180, 16, v180
	v_and_b32_e32 v163, 0xffff0000, v181
	v_lshlrev_b32_e32 v181, 16, v181
	v_add_f32_e32 v52, v52, v180
	v_add_f32_e32 v53, v53, v162
	v_add_f32_e32 v54, v54, v181
	v_add_f32_e32 v55, v55, v163
	v_mul_f32_e32 v180, v53, v53
	v_mul_f32_e32 v181, v55, v55
	v_fmac_f32_e32 v180, v52, v52
	v_fmac_f32_e32 v181, v54, v54
	v_add_f32_e32 v180, v180, v181
	v_add_f32_e32 v172, v172, v180
	v_cvt_pk_bf16_f32 v52, v52, v53
	v_cvt_pk_bf16_f32 v53, v54, v55
	v_and_b32_e32 v162, 0xffff0000, v182
	v_lshlrev_b32_e32 v182, 16, v182
	v_and_b32_e32 v163, 0xffff0000, v183
	v_lshlrev_b32_e32 v183, 16, v183
	v_add_f32_e32 v44, v44, v182
	v_add_f32_e32 v45, v45, v162
	v_add_f32_e32 v46, v46, v183
	v_add_f32_e32 v47, v47, v163
	v_mul_f32_e32 v182, v45, v45
	v_mul_f32_e32 v183, v47, v47
	v_fmac_f32_e32 v182, v44, v44
	v_fmac_f32_e32 v183, v46, v46
	v_add_f32_e32 v182, v182, v183
	v_add_f32_e32 v172, v172, v182
	v_cvt_pk_bf16_f32 v54, v44, v45
	v_cvt_pk_bf16_f32 v55, v46, v47
	v_mov_b32_e32 v60, v172
	v_add_u32_e32 v161, 0x58000, v160
	global_load_dwordx2 v[176:177], v161, s[16:17]
	global_load_dwordx2 v[178:179], v161, s[16:17] offset:32
	global_load_dwordx2 v[180:181], v161, s[16:17] offset:256
	global_load_dwordx2 v[182:183], v161, s[16:17] offset:288
	s_nop 1
	v_permlane16_swap_b32_e32 v64, v66
	v_permlane16_swap_b32_e32 v65, v67
	v_permlane16_swap_b32_e32 v52, v54
	v_permlane16_swap_b32_e32 v53, v55
	global_store_dwordx4 v174, v[64:67], s[18:19]
	global_store_dwordx4 v174, v[52:55], s[18:19] offset:256
	s_waitcnt vmcnt(26)
; __device__ __forceinline__ unsigned cvt_pk_bf16(float lo, float hi) { unsigned r; asm volatile("v_cvt_pk_bf16_f32 %0, %1, %2" : "=v"(r) : "v"(lo), "v"(hi)); return r; }
;     __device__ __forceinline__ void operator()(const f32x4 (&acc)[2][2][4][2], const pg8::Unit& u, int wr, int wc, int fr, int fq) const {
;     ...
;                     for (int bj = 0; bj < 2; ++bj)
; #pragma unroll
;                         for (int n = 0; n < 2; ++n) { const int col = col0 + bj * 128 + n * 16; f32x4 r;
;                             if (RESB) { const u32x2 rw = *(const u32x2*)(resb + (size_t)row * DM + col); r = (f32x4){bf2f(rw.x & 0xffff), bf2f(rw.x >> 16), bf2f(rw.y & 0xffff), bf2f(rw.y >> 16)}; }
;                             else r = *(const f32x4*)(rp + col);
;                             const f32x4 v = r + acc[ai][bj][m][n] * scale;
;                             if (OUTF) *(f32x4*)(out + (size_t)row * DM + col) = v;
;                             else { u32x2 w; w.x = cvt_pk_bf16(v[0], v[1]); w.y = cvt_pk_bf16(v[2], v[3]); *(u32x2*)(outb + (size_t)row * DM + col) = w;
;                                 s += (v[0] * v[0] + v[1] * v[1]) + (v[2] * v[2] + v[3] * v[3]); } }
	v_and_b32_e32 v162, 0xffff0000, v184
	v_lshlrev_b32_e32 v184, 16, v184
	v_and_b32_e32 v163, 0xffff0000, v185
	v_lshlrev_b32_e32 v185, 16, v185
	v_add_f32_e32 v48, v48, v184
	v_add_f32_e32 v49, v49, v162
	v_add_f32_e32 v50, v50, v185
	v_add_f32_e32 v51, v51, v163
	v_mul_f32_e32 v184, v49, v49
	v_mul_f32_e32 v185, v51, v51
	v_fmac_f32_e32 v184, v48, v48
	v_fmac_f32_e32 v185, v50, v50
	v_add_f32_e32 v184, v184, v185
	v_mov_b32_e32 v172, v184
	v_cvt_pk_bf16_f32 v48, v48, v49
	v_cvt_pk_bf16_f32 v49, v50, v51
	v_and_b32_e32 v162, 0xffff0000, v186
	v_lshlrev_b32_e32 v186, 16, v186
	v_and_b32_e32 v163, 0xffff0000, v187
	v_lshlrev_b32_e32 v187, 16, v187
	v_add_f32_e32 v40, v40, v186
	v_add_f32_e32 v41, v41, v162
	v_add_f32_e32 v42, v42, v187
	v_add_f32_e32 v43, v43, v163
	v_mul_f32_e32 v186, v41, v41
	v_mul_f32_e32 v187, v43, v43
	v_fmac_f32_e32 v186, v40, v40
	v_fmac_f32_e32 v187, v42, v42
	v_add_f32_e32 v186, v186, v187
	v_add_f32_e32 v172, v172, v186
	v_cvt_pk_bf16_f32 v50, v40, v41
	v_cvt_pk_bf16_f32 v51, v42, v43
	v_and_b32_e32 v162, 0xffff0000, v188
	v_lshlrev_b32_e32 v188, 16, v188
	v_and_b32_e32 v163, 0xffff0000, v189
	v_lshlrev_b32_e32 v189, 16, v189
	v_add_f32_e32 v36, v36, v188
	v_add_f32_e32 v37, v37, v162
	v_add_f32_e32 v38, v38, v189
	v_add_f32_e32 v39, v39, v163
	v_mul_f32_e32 v188, v37, v37
	v_mul_f32_e32 v189, v39, v39
	v_fmac_f32_e32 v188, v36, v36
	v_fmac_f32_e32 v189, v38, v38
	v_add_f32_e32 v188, v188, v189
	v_add_f32_e32 v172, v172, v188
	v_cvt_pk_bf16_f32 v36, v36, v37
	v_cvt_pk_bf16_f32 v37, v38, v39
	v_and_b32_e32 v162, 0xffff0000, v190
	v_lshlrev_b32_e32 v190, 16, v190
	v_and_b32_e32 v163, 0xffff0000, v191
	v_lshlrev_b32_e32 v191, 16, v191
	v_add_f32_e32 v28, v28, v190
	v_add_f32_e32 v29, v29, v162
	v_add_f32_e32 v30, v30, v191
	v_add_f32_e32 v31, v31, v163
	v_mul_f32_e32 v190, v29, v29
	v_mul_f32_e32 v191, v31, v31
	v_fmac_f32_e32 v190, v28, v28
	v_fmac_f32_e32 v191, v30, v30
	v_add_f32_e32 v190, v190, v191
	v_add_f32_e32 v172, v172, v190
	v_cvt_pk_bf16_f32 v38, v28, v29
	v_cvt_pk_bf16_f32 v39, v30, v31
	v_mov_b32_e32 v40, v172
	v_add_u32_e32 v161, 0x8000, v174
	s_nop 1
	v_permlane16_swap_b32_e32 v48, v50
	v_permlane16_swap_b32_e32 v49, v51
	v_permlane16_swap_b32_e32 v36, v38
	v_permlane16_swap_b32_e32 v37, v39
	global_store_dwordx4 v161, v[48:51], s[18:19]
	global_store_dwordx4 v161, v[36:39], s[18:19] offset:256
	s_waitcnt vmcnt(24)
	v_and_b32_e32 v162, 0xffff0000, v192
	v_lshlrev_b32_e32 v192, 16, v192
	v_and_b32_e32 v163, 0xffff0000, v193
	v_lshlrev_b32_e32 v193, 16, v193
	v_add_f32_e32 v32, v32, v192
	v_add_f32_e32 v33, v33, v162
	v_add_f32_e32 v34, v34, v193
	v_add_f32_e32 v35, v35, v163
	v_mul_f32_e32 v192, v33, v33
	v_mul_f32_e32 v193, v35, v35
	v_fmac_f32_e32 v192, v32, v32
	v_fmac_f32_e32 v193, v34, v34
	v_add_f32_e32 v192, v192, v193
	v_mov_b32_e32 v172, v192
	v_cvt_pk_bf16_f32 v32, v32, v33
	v_cvt_pk_bf16_f32 v33, v34, v35
	v_and_b32_e32 v162, 0xffff0000, v194
	v_lshlrev_b32_e32 v194, 16, v194
	v_and_b32_e32 v163, 0xffff0000, v195
	v_lshlrev_b32_e32 v195, 16, v195
	v_add_f32_e32 v24, v24, v194
	v_add_f32_e32 v25, v25, v162
	v_add_f32_e32 v26, v26, v195
	v_add_f32_e32 v27, v27, v163
	v_mul_f32_e32 v194, v25, v25
	v_mul_f32_e32 v195, v27, v27
	v_fmac_f32_e32 v194, v24, v24
	v_fmac_f32_e32 v195, v26, v26
	v_add_f32_e32 v194, v194, v195
	v_add_f32_e32 v172, v172, v194
	v_cvt_pk_bf16_f32 v34, v24, v25
	v_cvt_pk_bf16_f32 v35, v26, v27
	v_and_b32_e32 v162, 0xffff0000, v196
	v_lshlrev_b32_e32 v196, 16, v196
	v_and_b32_e32 v163, 0xffff0000, v197
	v_lshlrev_b32_e32 v197, 16, v197
	v_add_f32_e32 v20, v20, v196
	v_add_f32_e32 v21, v21, v162
	v_add_f32_e32 v22, v22, v197
	v_add_f32_e32 v23, v23, v163
	v_mul_f32_e32 v196, v21, v21
	v_mul_f32_e32 v197, v23, v23
	v_fmac_f32_e32 v196, v20, v20
	v_fmac_f32_e32 v197, v22, v22
	v_add_f32_e32 v196, v196, v197
	v_add_f32_e32 v172, v172, v196
	v_cvt_pk_bf16_f32 v20, v20, v21
	v_cvt_pk_bf16_f32 v21, v22, v23
	v_and_b32_e32 v162, 0xffff0000, v198
	v_lshlrev_b32_e32 v198, 16, v198
	v_and_b32_e32 v163, 0xffff0000, v199
	v_lshlrev_b32_e32 v199, 16, v199
	v_add_f32_e32 v12, v12, v198
	v_add_f32_e32 v13, v13, v162
	v_add_f32_e32 v14, v14, v199
	v_add_f32_e32 v15, v15, v163
	v_mul_f32_e32 v198, v13, v13
	v_mul_f32_e32 v199, v15, v15
	v_fmac_f32_e32 v198, v12, v12
	v_fmac_f32_e32 v199, v14, v14
	v_add_f32_e32 v198, v198, v199
	v_add_f32_e32 v172, v172, v198
	v_cvt_pk_bf16_f32 v22, v12, v13
	v_cvt_pk_bf16_f32 v23, v14, v15
	v_mov_b32_e32 v24, v172
	v_add_u32_e32 v161, 0x10000, v174
	s_nop 1
	v_permlane16_swap_b32_e32 v32, v34
	v_permlane16_swap_b32_e32 v33, v35
	v_permlane16_swap_b32_e32 v20, v22
	v_permlane16_swap_b32_e32 v21, v23
	global_store_dwordx4 v161, v[32:35], s[18:19]
	global_store_dwordx4 v161, v[20:23], s[18:19] offset:256
	s_waitcnt vmcnt(22)
; __device__ __forceinline__ unsigned cvt_pk_bf16(float lo, float hi) { unsigned r; asm volatile("v_cvt_pk_bf16_f32 %0, %1, %2" : "=v"(r) : "v"(lo), "v"(hi)); return r; }
;     __device__ __forceinline__ void operator()(const f32x4 (&acc)[2][2][4][2], const pg8::Unit& u, int wr, int wc, int fr, int fq) const {
;     ...
;                     for (int bj = 0; bj < 2; ++bj)
; #pragma unroll
;                         for (int n = 0; n < 2; ++n) { const int col = col0 + bj * 128 + n * 16; f32x4 r;
;                             if (RESB) { const u32x2 rw = *(const u32x2*)(resb + (size_t)row * DM + col); r = (f32x4){bf2f(rw.x & 0xffff), bf2f(rw.x >> 16), bf2f(rw.y & 0xffff), bf2f(rw.y >> 16)}; }
;                             else r = *(const f32x4*)(rp + col);
;                             const f32x4 v = r + acc[ai][bj][m][n] * scale;
;                             if (OUTF) *(f32x4*)(out + (size_t)row * DM + col) = v;
;                             else { u32x2 w; w.x = cvt_pk_bf16(v[0], v[1]); w.y = cvt_pk_bf16(v[2], v[3]); *(u32x2*)(outb + (size_t)row * DM + col) = w;
;                                 s += (v[0] * v[0] + v[1] * v[1]) + (v[2] * v[2] + v[3] * v[3]); } }
	v_and_b32_e32 v162, 0xffff0000, v200
	v_lshlrev_b32_e32 v200, 16, v200
	v_and_b32_e32 v163, 0xffff0000, v201
	v_lshlrev_b32_e32 v201, 16, v201
	v_add_f32_e32 v16, v16, v200
	v_add_f32_e32 v17, v17, v162
	v_add_f32_e32 v18, v18, v201
	v_add_f32_e32 v19, v19, v163
	v_mul_f32_e32 v200, v17, v17
	v_mul_f32_e32 v201, v19, v19
	v_fmac_f32_e32 v200, v16, v16
	v_fmac_f32_e32 v201, v18, v18
	v_add_f32_e32 v200, v200, v201
	v_mov_b32_e32 v172, v200
	v_cvt_pk_bf16_f32 v16, v16, v17
	v_cvt_pk_bf16_f32 v17, v18, v19
	v_and_b32_e32 v162, 0xffff0000, v202
	v_lshlrev_b32_e32 v202, 16, v202
	v_and_b32_e32 v163, 0xffff0000, v203
	v_lshlrev_b32_e32 v203, 16, v203
	v_add_f32_e32 v8, v8, v202
	v_add_f32_e32 v9, v9, v162
	v_add_f32_e32 v10, v10, v203
	v_add_f32_e32 v11, v11, v163
	v_mul_f32_e32 v202, v9, v9
	v_mul_f32_e32 v203, v11, v11
	v_fmac_f32_e32 v202, v8, v8
	v_fmac_f32_e32 v203, v10, v10
	v_add_f32_e32 v202, v202, v203
	v_add_f32_e32 v172, v172, v202
	v_cvt_pk_bf16_f32 v18, v8, v9
	v_cvt_pk_bf16_f32 v19, v10, v11
	v_and_b32_e32 v162, 0xffff0000, v204
	v_lshlrev_b32_e32 v204, 16, v204
	v_and_b32_e32 v163, 0xffff0000, v205
	v_lshlrev_b32_e32 v205, 16, v205
	v_add_f32_e32 v4, v4, v204
	v_add_f32_e32 v5, v5, v162
	v_add_f32_e32 v6, v6, v205
	v_add_f32_e32 v7, v7, v163
	v_mul_f32_e32 v204, v5, v5
	v_mul_f32_e32 v205, v7, v7
	v_fmac_f32_e32 v204, v4, v4
	v_fmac_f32_e32 v205, v6, v6
	v_add_f32_e32 v204, v204, v205
	v_add_f32_e32 v172, v172, v204
	v_cvt_pk_bf16_f32 v4, v4, v5
	v_cvt_pk_bf16_f32 v5, v6, v7
	v_and_b32_e32 v162, 0xffff0000, v206
	v_lshlrev_b32_e32 v206, 16, v206
	v_and_b32_e32 v163, 0xffff0000, v207
	v_lshlrev_b32_e32 v207, 16, v207
	v_add_f32_e32 v0, v0, v206
	v_add_f32_e32 v1, v1, v162
	v_add_f32_e32 v2, v2, v207
	v_add_f32_e32 v3, v3, v163
	v_mul_f32_e32 v206, v1, v1
	v_mul_f32_e32 v207, v3, v3
	v_fmac_f32_e32 v206, v0, v0
	v_fmac_f32_e32 v207, v2, v2
	v_add_f32_e32 v206, v206, v207
	v_add_f32_e32 v172, v172, v206
	v_cvt_pk_bf16_f32 v6, v0, v1
	v_cvt_pk_bf16_f32 v7, v2, v3
	v_mov_b32_e32 v8, v172
	v_add_u32_e32 v161, 0x18000, v174
	s_nop 1
	v_permlane16_swap_b32_e32 v16, v18
	v_permlane16_swap_b32_e32 v17, v19
	v_permlane16_swap_b32_e32 v4, v6
	v_permlane16_swap_b32_e32 v5, v7
	global_store_dwordx4 v161, v[16:19], s[18:19]
	global_store_dwordx4 v161, v[4:7], s[18:19] offset:256
	s_waitcnt vmcnt(20)
	v_and_b32_e32 v162, 0xffff0000, v208
	v_lshlrev_b32_e32 v208, 16, v208
	v_and_b32_e32 v163, 0xffff0000, v209
	v_lshlrev_b32_e32 v209, 16, v209
	v_add_f32_e32 v124, v124, v208
	v_add_f32_e32 v125, v125, v162
	v_add_f32_e32 v126, v126, v209
	v_add_f32_e32 v127, v127, v163
	v_mul_f32_e32 v208, v125, v125
	v_mul_f32_e32 v209, v127, v127
	v_fmac_f32_e32 v208, v124, v124
	v_fmac_f32_e32 v209, v126, v126
	v_add_f32_e32 v208, v208, v209
	v_mov_b32_e32 v172, v208
	v_cvt_pk_bf16_f32 v124, v124, v125
	v_cvt_pk_bf16_f32 v125, v126, v127
	v_and_b32_e32 v162, 0xffff0000, v210
	v_lshlrev_b32_e32 v210, 16, v210
	v_and_b32_e32 v163, 0xffff0000, v211
	v_lshlrev_b32_e32 v211, 16, v211
	v_add_f32_e32 v120, v120, v210
	v_add_f32_e32 v121, v121, v162
	v_add_f32_e32 v122, v122, v211
	v_add_f32_e32 v123, v123, v163
	v_mul_f32_e32 v210, v121, v121
	v_mul_f32_e32 v211, v123, v123
	v_fmac_f32_e32 v210, v120, v120
	v_fmac_f32_e32 v211, v122, v122
	v_add_f32_e32 v210, v210, v211
	v_add_f32_e32 v172, v172, v210
	v_cvt_pk_bf16_f32 v126, v120, v121
	v_cvt_pk_bf16_f32 v127, v122, v123
	v_and_b32_e32 v162, 0xffff0000, v212
	v_lshlrev_b32_e32 v212, 16, v212
	v_and_b32_e32 v163, 0xffff0000, v213
	v_lshlrev_b32_e32 v213, 16, v213
	v_add_f32_e32 v116, v116, v212
	v_add_f32_e32 v117, v117, v162
	v_add_f32_e32 v118, v118, v213
	v_add_f32_e32 v119, v119, v163
	v_mul_f32_e32 v212, v117, v117
	v_mul_f32_e32 v213, v119, v119
	v_fmac_f32_e32 v212, v116, v116
	v_fmac_f32_e32 v213, v118, v118
	v_add_f32_e32 v212, v212, v213
	v_add_f32_e32 v172, v172, v212
	v_cvt_pk_bf16_f32 v116, v116, v117
	v_cvt_pk_bf16_f32 v117, v118, v119
	v_and_b32_e32 v162, 0xffff0000, v214
	v_lshlrev_b32_e32 v214, 16, v214
	v_and_b32_e32 v163, 0xffff0000, v215
	v_lshlrev_b32_e32 v215, 16, v215
	v_add_f32_e32 v112, v112, v214
	v_add_f32_e32 v113, v113, v162
	v_add_f32_e32 v114, v114, v215
	v_add_f32_e32 v115, v115, v163
	v_mul_f32_e32 v214, v113, v113
	v_mul_f32_e32 v215, v115, v115
	v_fmac_f32_e32 v214, v112, v112
	v_fmac_f32_e32 v215, v114, v114
	v_add_f32_e32 v214, v214, v215
	v_add_f32_e32 v172, v172, v214
	v_cvt_pk_bf16_f32 v118, v112, v113
	v_cvt_pk_bf16_f32 v119, v114, v115
	v_mov_b32_e32 v120, v172
	v_add_u32_e32 v161, 0x40000, v174
	s_nop 1
	v_permlane16_swap_b32_e32 v124, v126
	v_permlane16_swap_b32_e32 v125, v127
	v_permlane16_swap_b32_e32 v116, v118
	v_permlane16_swap_b32_e32 v117, v119
	global_store_dwordx4 v161, v[124:127], s[18:19]
	global_store_dwordx4 v161, v[116:119], s[18:19] offset:256
	s_waitcnt vmcnt(18)
; __device__ __forceinline__ unsigned cvt_pk_bf16(float lo, float hi) { unsigned r; asm volatile("v_cvt_pk_bf16_f32 %0, %1, %2" : "=v"(r) : "v"(lo), "v"(hi)); return r; }
;     __device__ __forceinline__ void operator()(const f32x4 (&acc)[2][2][4][2], const pg8::Unit& u, int wr, int wc, int fr, int fq) const {
;     ...
;                     for (int bj = 0; bj < 2; ++bj)
; #pragma unroll
;                         for (int n = 0; n < 2; ++n) { const int col = col0 + bj * 128 + n * 16; f32x4 r;
;                             if (RESB) { const u32x2 rw = *(const u32x2*)(resb + (size_t)row * DM + col); r = (f32x4){bf2f(rw.x & 0xffff), bf2f(rw.x >> 16), bf2f(rw.y & 0xffff), bf2f(rw.y >> 16)}; }
;                             else r = *(const f32x4*)(rp + col);
;                             const f32x4 v = r + acc[ai][bj][m][n] * scale;
;                             if (OUTF) *(f32x4*)(out + (size_t)row * DM + col) = v;
;                             else { u32x2 w; w.x = cvt_pk_bf16(v[0], v[1]); w.y = cvt_pk_bf16(v[2], v[3]); *(u32x2*)(outb + (size_t)row * DM + col) = w;
;                                 s += (v[0] * v[0] + v[1] * v[1]) + (v[2] * v[2] + v[3] * v[3]); } }
	v_and_b32_e32 v162, 0xffff0000, v144
	v_lshlrev_b32_e32 v144, 16, v144
	v_and_b32_e32 v163, 0xffff0000, v145
	v_lshlrev_b32_e32 v145, 16, v145
	v_add_f32_e32 v108, v108, v144
	v_add_f32_e32 v109, v109, v162
	v_add_f32_e32 v110, v110, v145
	v_add_f32_e32 v111, v111, v163
	v_mul_f32_e32 v144, v109, v109
	v_mul_f32_e32 v145, v111, v111
	v_fmac_f32_e32 v144, v108, v108
	v_fmac_f32_e32 v145, v110, v110
	v_add_f32_e32 v144, v144, v145
	v_mov_b32_e32 v172, v144
	v_cvt_pk_bf16_f32 v108, v108, v109
	v_cvt_pk_bf16_f32 v109, v110, v111
	v_and_b32_e32 v162, 0xffff0000, v146
	v_lshlrev_b32_e32 v146, 16, v146
	v_and_b32_e32 v163, 0xffff0000, v147
	v_lshlrev_b32_e32 v147, 16, v147
	v_add_f32_e32 v104, v104, v146
	v_add_f32_e32 v105, v105, v162
	v_add_f32_e32 v106, v106, v147
	v_add_f32_e32 v107, v107, v163
	v_mul_f32_e32 v146, v105, v105
	v_mul_f32_e32 v147, v107, v107
	v_fmac_f32_e32 v146, v104, v104
	v_fmac_f32_e32 v147, v106, v106
	v_add_f32_e32 v146, v146, v147
	v_add_f32_e32 v172, v172, v146
	v_cvt_pk_bf16_f32 v110, v104, v105
	v_cvt_pk_bf16_f32 v111, v106, v107
	v_and_b32_e32 v162, 0xffff0000, v148
	v_lshlrev_b32_e32 v148, 16, v148
	v_and_b32_e32 v163, 0xffff0000, v149
	v_lshlrev_b32_e32 v149, 16, v149
	v_add_f32_e32 v100, v100, v148
	v_add_f32_e32 v101, v101, v162
	v_add_f32_e32 v102, v102, v149
	v_add_f32_e32 v103, v103, v163
	v_mul_f32_e32 v148, v101, v101
	v_mul_f32_e32 v149, v103, v103
	v_fmac_f32_e32 v148, v100, v100
	v_fmac_f32_e32 v149, v102, v102
	v_add_f32_e32 v148, v148, v149
	v_add_f32_e32 v172, v172, v148
	v_cvt_pk_bf16_f32 v100, v100, v101
	v_cvt_pk_bf16_f32 v101, v102, v103
	v_and_b32_e32 v162, 0xffff0000, v150
	v_lshlrev_b32_e32 v150, 16, v150
	v_and_b32_e32 v163, 0xffff0000, v151
	v_lshlrev_b32_e32 v151, 16, v151
	v_add_f32_e32 v96, v96, v150
	v_add_f32_e32 v97, v97, v162
	v_add_f32_e32 v98, v98, v151
	v_add_f32_e32 v99, v99, v163
	v_mul_f32_e32 v150, v97, v97
	v_mul_f32_e32 v151, v99, v99
	v_fmac_f32_e32 v150, v96, v96
	v_fmac_f32_e32 v151, v98, v98
	v_add_f32_e32 v150, v150, v151
	v_add_f32_e32 v172, v172, v150
	v_cvt_pk_bf16_f32 v102, v96, v97
	v_cvt_pk_bf16_f32 v103, v98, v99
	v_mov_b32_e32 v104, v172
	v_add_u32_e32 v161, 0x48000, v174
	s_nop 1
	v_permlane16_swap_b32_e32 v108, v110
	v_permlane16_swap_b32_e32 v109, v111
	v_permlane16_swap_b32_e32 v100, v102
	v_permlane16_swap_b32_e32 v101, v103
	global_store_dwordx4 v161, v[108:111], s[18:19]
	global_store_dwordx4 v161, v[100:103], s[18:19] offset:256
	s_waitcnt vmcnt(16)
	v_and_b32_e32 v162, 0xffff0000, v152
	v_lshlrev_b32_e32 v152, 16, v152
	v_and_b32_e32 v163, 0xffff0000, v153
	v_lshlrev_b32_e32 v153, 16, v153
	v_add_f32_e32 v92, v92, v152
	v_add_f32_e32 v93, v93, v162
	v_add_f32_e32 v94, v94, v153
	v_add_f32_e32 v95, v95, v163
	v_mul_f32_e32 v152, v93, v93
	v_mul_f32_e32 v153, v95, v95
	v_fmac_f32_e32 v152, v92, v92
	v_fmac_f32_e32 v153, v94, v94
	v_add_f32_e32 v152, v152, v153
	v_mov_b32_e32 v172, v152
	v_cvt_pk_bf16_f32 v92, v92, v93
	v_cvt_pk_bf16_f32 v93, v94, v95
	v_and_b32_e32 v162, 0xffff0000, v154
	v_lshlrev_b32_e32 v154, 16, v154
	v_and_b32_e32 v163, 0xffff0000, v155
	v_lshlrev_b32_e32 v155, 16, v155
	v_add_f32_e32 v88, v88, v154
	v_add_f32_e32 v89, v89, v162
	v_add_f32_e32 v90, v90, v155
	v_add_f32_e32 v91, v91, v163
	v_mul_f32_e32 v154, v89, v89
	v_mul_f32_e32 v155, v91, v91
	v_fmac_f32_e32 v154, v88, v88
	v_fmac_f32_e32 v155, v90, v90
	v_add_f32_e32 v154, v154, v155
	v_add_f32_e32 v172, v172, v154
	v_cvt_pk_bf16_f32 v94, v88, v89
	v_cvt_pk_bf16_f32 v95, v90, v91
	v_and_b32_e32 v162, 0xffff0000, v156
	v_lshlrev_b32_e32 v156, 16, v156
	v_and_b32_e32 v163, 0xffff0000, v157
	v_lshlrev_b32_e32 v157, 16, v157
	v_add_f32_e32 v84, v84, v156
	v_add_f32_e32 v85, v85, v162
	v_add_f32_e32 v86, v86, v157
	v_add_f32_e32 v87, v87, v163
	v_mul_f32_e32 v156, v85, v85
	v_mul_f32_e32 v157, v87, v87
	v_fmac_f32_e32 v156, v84, v84
	v_fmac_f32_e32 v157, v86, v86
	v_add_f32_e32 v156, v156, v157
	v_add_f32_e32 v172, v172, v156
	v_cvt_pk_bf16_f32 v84, v84, v85
	v_cvt_pk_bf16_f32 v85, v86, v87
	v_and_b32_e32 v162, 0xffff0000, v158
	v_lshlrev_b32_e32 v158, 16, v158
	v_and_b32_e32 v163, 0xffff0000, v159
	v_lshlrev_b32_e32 v159, 16, v159
	v_add_f32_e32 v80, v80, v158
	v_add_f32_e32 v81, v81, v162
	v_add_f32_e32 v82, v82, v159
	v_add_f32_e32 v83, v83, v163
	v_mul_f32_e32 v158, v81, v81
	v_mul_f32_e32 v159, v83, v83
	v_fmac_f32_e32 v158, v80, v80
	v_fmac_f32_e32 v159, v82, v82
	v_add_f32_e32 v158, v158, v159
	v_add_f32_e32 v172, v172, v158
	v_cvt_pk_bf16_f32 v86, v80, v81
	v_cvt_pk_bf16_f32 v87, v82, v83
	v_mov_b32_e32 v88, v172
	v_add_u32_e32 v161, 0x50000, v174
	s_nop 1
	v_permlane16_swap_b32_e32 v92, v94
	v_permlane16_swap_b32_e32 v93, v95
	v_permlane16_swap_b32_e32 v84, v86
	v_permlane16_swap_b32_e32 v85, v87
	global_store_dwordx4 v161, v[92:95], s[18:19]
	global_store_dwordx4 v161, v[84:87], s[18:19] offset:256
	s_waitcnt vmcnt(14)
; __device__ __forceinline__ unsigned cvt_pk_bf16(float lo, float hi) { unsigned r; asm volatile("v_cvt_pk_bf16_f32 %0, %1, %2" : "=v"(r) : "v"(lo), "v"(hi)); return r; }
;     __device__ __forceinline__ void operator()(const f32x4 (&acc)[2][2][4][2], const pg8::Unit& u, int wr, int wc, int fr, int fq) const {
;     ...
;                     for (int bj = 0; bj < 2; ++bj)
; #pragma unroll
;                         for (int n = 0; n < 2; ++n) { const int col = col0 + bj * 128 + n * 16; f32x4 r;
;                             if (RESB) { const u32x2 rw = *(const u32x2*)(resb + (size_t)row * DM + col); r = (f32x4){bf2f(rw.x & 0xffff), bf2f(rw.x >> 16), bf2f(rw.y & 0xffff), bf2f(rw.y >> 16)}; }
;                             else r = *(const f32x4*)(rp + col);
;                             const f32x4 v = r + acc[ai][bj][m][n] * scale;
;                             if (OUTF) *(f32x4*)(out + (size_t)row * DM + col) = v;
;                             else { u32x2 w; w.x = cvt_pk_bf16(v[0], v[1]); w.y = cvt_pk_bf16(v[2], v[3]); *(u32x2*)(outb + (size_t)row * DM + col) = w;
;                                 s += (v[0] * v[0] + v[1] * v[1]) + (v[2] * v[2] + v[3] * v[3]); } }
;                     if (!OUTF) { s += __shfl_xor(s, 16); s += __shfl_xor(s, 32); if (fq == 0) atomicAdd(ss + row, s); }
;                 }
	v_and_b32_e32 v162, 0xffff0000, v176
	v_lshlrev_b32_e32 v176, 16, v176
	v_and_b32_e32 v163, 0xffff0000, v177
	v_lshlrev_b32_e32 v177, 16, v177
	v_add_f32_e32 v76, v76, v176
	v_add_f32_e32 v77, v77, v162
	v_add_f32_e32 v78, v78, v177
	v_add_f32_e32 v79, v79, v163
	v_mul_f32_e32 v176, v77, v77
	v_mul_f32_e32 v177, v79, v79
	v_fmac_f32_e32 v176, v76, v76
	v_fmac_f32_e32 v177, v78, v78
	v_add_f32_e32 v176, v176, v177
	v_mov_b32_e32 v172, v176
	v_cvt_pk_bf16_f32 v76, v76, v77
	v_cvt_pk_bf16_f32 v77, v78, v79
	v_and_b32_e32 v162, 0xffff0000, v178
	v_lshlrev_b32_e32 v178, 16, v178
	v_and_b32_e32 v163, 0xffff0000, v179
	v_lshlrev_b32_e32 v179, 16, v179
	v_add_f32_e32 v72, v72, v178
	v_add_f32_e32 v73, v73, v162
	v_add_f32_e32 v74, v74, v179
	v_add_f32_e32 v75, v75, v163
	v_mul_f32_e32 v178, v73, v73
	v_mul_f32_e32 v179, v75, v75
	v_fmac_f32_e32 v178, v72, v72
	v_fmac_f32_e32 v179, v74, v74
	v_add_f32_e32 v178, v178, v179
	v_add_f32_e32 v172, v172, v178
	v_cvt_pk_bf16_f32 v78, v72, v73
	v_cvt_pk_bf16_f32 v79, v74, v75
	v_and_b32_e32 v162, 0xffff0000, v180
	v_lshlrev_b32_e32 v180, 16, v180
	v_and_b32_e32 v163, 0xffff0000, v181
	v_lshlrev_b32_e32 v181, 16, v181
	v_add_f32_e32 v68, v68, v180
	v_add_f32_e32 v69, v69, v162
	v_add_f32_e32 v70, v70, v181
	v_add_f32_e32 v71, v71, v163
	v_mul_f32_e32 v180, v69, v69
	v_mul_f32_e32 v181, v71, v71
	v_fmac_f32_e32 v180, v68, v68
	v_fmac_f32_e32 v181, v70, v70
	v_add_f32_e32 v180, v180, v181
	v_add_f32_e32 v172, v172, v180
	v_cvt_pk_bf16_f32 v68, v68, v69
	v_cvt_pk_bf16_f32 v69, v70, v71
	v_and_b32_e32 v162, 0xffff0000, v182
	v_lshlrev_b32_e32 v182, 16, v182
	v_and_b32_e32 v163, 0xffff0000, v183
	v_lshlrev_b32_e32 v183, 16, v183
	v_add_f32_e32 v56, v56, v182
	v_add_f32_e32 v57, v57, v162
	v_add_f32_e32 v58, v58, v183
	v_add_f32_e32 v59, v59, v163
	v_mul_f32_e32 v182, v57, v57
	v_mul_f32_e32 v183, v59, v59
	v_fmac_f32_e32 v182, v56, v56
	v_fmac_f32_e32 v183, v58, v58
	v_add_f32_e32 v182, v182, v183
	v_add_f32_e32 v172, v172, v182
	v_cvt_pk_bf16_f32 v70, v56, v57
	v_cvt_pk_bf16_f32 v71, v58, v59
	v_mov_b32_e32 v72, v172
	v_add_u32_e32 v161, 0x58000, v174
	s_nop 1
	v_permlane16_swap_b32_e32 v76, v78
	v_permlane16_swap_b32_e32 v77, v79
	v_permlane16_swap_b32_e32 v68, v70
	v_permlane16_swap_b32_e32 v69, v71
	global_store_dwordx4 v161, v[76:79], s[18:19]
	global_store_dwordx4 v161, v[68:71], s[18:19] offset:256
	v_xor_b32_e32 v173, 16, v170
	v_lshlrev_b32_e32 v173, 2, v173
	ds_bpermute_b32 v61, v173, v60
	ds_bpermute_b32 v41, v173, v40
	ds_bpermute_b32 v25, v173, v24
	ds_bpermute_b32 v9, v173, v8
	ds_bpermute_b32 v121, v173, v120
	ds_bpermute_b32 v105, v173, v104
	ds_bpermute_b32 v89, v173, v88
	ds_bpermute_b32 v73, v173, v72
	s_waitcnt lgkmcnt(0)
	v_add_f32_e32 v60, v60, v61
	v_add_f32_e32 v40, v40, v41
	v_add_f32_e32 v24, v24, v25
	v_add_f32_e32 v8, v8, v9
	v_add_f32_e32 v120, v120, v121
	v_add_f32_e32 v104, v104, v105
	v_add_f32_e32 v88, v88, v89
	v_add_f32_e32 v72, v72, v73
	v_xor_b32_e32 v173, 32, v170
	v_lshlrev_b32_e32 v173, 2, v173
	ds_bpermute_b32 v61, v173, v60
	ds_bpermute_b32 v41, v173, v40
	ds_bpermute_b32 v25, v173, v24
	ds_bpermute_b32 v9, v173, v8
	ds_bpermute_b32 v121, v173, v120
	ds_bpermute_b32 v105, v173, v104
	ds_bpermute_b32 v89, v173, v88
	ds_bpermute_b32 v73, v173, v72
	s_waitcnt lgkmcnt(0)
	v_add_f32_e32 v60, v60, v61
	v_add_f32_e32 v40, v40, v41
	v_add_f32_e32 v24, v24, v25
	v_add_f32_e32 v8, v8, v9
	v_add_f32_e32 v120, v120, v121
	v_add_f32_e32 v104, v104, v105
	v_add_f32_e32 v88, v88, v89
	v_add_f32_e32 v72, v72, v73
	v_lshl_add_u32 v160, s46, 8, v164
	v_lshlrev_b32_e32 v160, 2, v160
	s_and_saveexec_b64 s[0:1], s[8:9]
	global_atomic_add_f32 v160, v60, s[20:21]
	global_atomic_add_f32 v160, v40, s[20:21] offset:64
	global_atomic_add_f32 v160, v24, s[20:21] offset:128
	global_atomic_add_f32 v160, v8, s[20:21] offset:192
	global_atomic_add_f32 v160, v120, s[20:21] offset:512
	global_atomic_add_f32 v160, v104, s[20:21] offset:576
	global_atomic_add_f32 v160, v88, s[20:21] offset:640
	global_atomic_add_f32 v160, v72, s[20:21] offset:704
	s_or_b64 exec, exec, s[0:1]
	s_branch .Lp7e_done
